# attention queue pop prefetched at the start of each unit's final-PV (atomic latency and O-store acks no longer exposed at the pop) + first-iteration vmcnt relaxation in Down/Out GEMMs
# speedup vs baseline: 1.0023x; 1.0023x over previous
; template <int MODE> __device__ __forceinline__ void attn_unit4(LAS unsigned char* lds, const int uidx, const AttnArgs& A) {
;     ...
;             const float sx = wave_sum(A.dl[lane] * A.dl[64 + lane], lane), sy = wave_sum(A.dl[128 + lane] * A.dl[192 + lane], lane);
;             const float lam = __expf(sx) - __expf(sy) + A.lam_init;
; __global__ void __launch_bounds__(NTHR, 2) mega_fwd(KArgs a) {
;     ...
;         {
;             AttnArgs A{U, KC, VC, (bf16_t*)(ws + WS_O), a.in[3], a.in[9] + (size_t)l * 256, a.in[10] + (size_t)l * 128, a.in[11] + (size_t)l * 4, 0.8f - 0.6f * __expf(-0.3f * (float)l)};
;             constexpr int NA = NSEQ * 4 * 65, NC = NSEQ * 2 * 65, NB = NSEQ * 2 * 65;
;             unsigned* qhead = (unsigned*)ws + CW_QUEUE + 64 * l;
;             for (;;) {
;                 if (threadIdx.x == 0) MISC[16] = atomicAdd(qhead, 1u);
.LBB0_907:
	s_or_b64 exec, exec, s[0:1]
	v_readlane_b32 s0, v254, 62
	s_add_u32 s10, s20, 0x2ea00000
	v_readlane_b32 s1, v254, 63
	v_readlane_b32 s68, v254, 33
	s_addc_u32 s11, s21, 0
	s_lshl_b64 s[0:1], s[0:1], 2
	v_readlane_b32 s76, v254, 41
	v_readlane_b32 s77, v254, 42
	s_add_u32 s0, s76, s0
	s_addc_u32 s1, s77, s1
	v_readlane_b32 s69, v254, 34
	v_readlane_b32 s70, v254, 35
	v_readlane_b32 s71, v254, 36
	v_readlane_b32 s72, v254, 37
	v_readlane_b32 s73, v254, 38
	v_readlane_b32 s74, v254, 39
	v_readlane_b32 s75, v254, 40
	v_readlane_b32 s78, v254, 43
	v_readlane_b32 s79, v254, 44
	v_readlane_b32 s80, v254, 45
	v_readlane_b32 s81, v254, 46
	v_readlane_b32 s82, v254, 47
	v_readlane_b32 s83, v254, 48
	v_writelane_b32 v254, s0, 62
	s_waitcnt lgkmcnt(0)
	v_mov_b32_e32 v2, 0x3f4ccccd
	v_writelane_b32 v254, s1, 63
	s_barrier
	v_readlane_b32 s0, v254, 59
	v_readlane_b32 s1, v254, 60
	v_readlane_b32 s4, v254, 55
	s_lshl_b64 s[0:1], s[0:1], 2
	v_readlane_b32 s5, v254, 56
	s_add_u32 s60, s78, s0
	v_cvt_f32_u32_e32 v0, s4
	s_addc_u32 s61, s79, s1
	s_lshl_b64 s[0:1], s[4:5], 4
	s_add_u32 s68, s80, s0
	s_addc_u32 s89, s81, s1
	s_lshl_b32 s30, s4, 6
	s_lshl_b64 s[0:1], s[30:31], 2
	v_mul_f32_e32 v0, 0xbe99999a, v0
	s_add_u32 s20, s20, s0
	v_mul_f32_e32 v0, 0x3fb8aa3b, v0
	s_addc_u32 s21, s21, s1
	v_exp_f32_e32 v0, v0
	s_cmp_eq_u32 s4, 1
	s_cselect_b64 s[82:83], -1, 0
	s_add_u32 s0, s16, 0x1000
	v_writelane_b32 v254, s0, 59
	s_addc_u32 s0, s17, 0
	v_writelane_b32 v255, s0, 0
	s_add_u32 s0, s16, 0x4df00
	v_fmamk_f32 v189, v0, 0xbf19999a, v2
	v_writelane_b32 v254, s0, 61
	s_addc_u32 s0, s17, 0
	v_sub_f32_e32 v191, 1.0, v189
	v_writelane_b32 v255, s0, 2
	v_readlane_b32 s84, v254, 62
	v_readlane_b32 s85, v254, 63
	v_and_b32_e32 v228, 63, v252
	v_lshlrev_b32_e32 v228, 2, v228
	s_nop 4
	global_load_dword v229, v228, s[84:85]
	global_load_dword v230, v228, s[84:85] offset:256
	global_load_dword v231, v228, s[84:85] offset:512
	global_load_dword v232, v228, s[84:85] offset:768
	s_waitcnt vmcnt(0)
	v_mul_f32_e32 v233, v229, v230
	v_xor_b32_e32 v234, 4, v228
	ds_bpermute_b32 v234, v234, v233
	s_waitcnt lgkmcnt(0)
	v_fmac_f32_e32 v234, v229, v230
	v_xor_b32_e32 v233, 8, v228
	ds_bpermute_b32 v233, v233, v234
	s_waitcnt lgkmcnt(0)
	v_add_f32_e32 v234, v234, v233
	v_xor_b32_e32 v233, 16, v228
	ds_bpermute_b32 v233, v233, v234
	s_waitcnt lgkmcnt(0)
	v_add_f32_e32 v234, v234, v233
	v_xor_b32_e32 v233, 32, v228
	ds_bpermute_b32 v233, v233, v234
	s_waitcnt lgkmcnt(0)
	v_add_f32_e32 v234, v234, v233
	v_xor_b32_e32 v233, 64, v228
	ds_bpermute_b32 v233, v233, v234
	s_waitcnt lgkmcnt(0)
	v_add_f32_e32 v234, v234, v233
	v_xor_b32_e32 v233, 0x80, v228
	ds_bpermute_b32 v233, v233, v234
	s_waitcnt lgkmcnt(0)
	v_add_f32_e32 v234, v234, v233
	v_mul_f32_e32 v234, 0x3fb8aa3b, v234
	v_exp_f32_e32 v235, v234
	v_mul_f32_e32 v233, v231, v232
	v_xor_b32_e32 v236, 4, v228
	ds_bpermute_b32 v236, v236, v233
	s_waitcnt lgkmcnt(0)
	v_fmac_f32_e32 v236, v231, v232
	v_xor_b32_e32 v233, 8, v228
	ds_bpermute_b32 v233, v233, v236
	s_waitcnt lgkmcnt(0)
	v_add_f32_e32 v236, v236, v233
	v_xor_b32_e32 v233, 16, v228
	ds_bpermute_b32 v233, v233, v236
	s_waitcnt lgkmcnt(0)
	v_add_f32_e32 v236, v236, v233
	v_xor_b32_e32 v233, 32, v228
	ds_bpermute_b32 v233, v233, v236
	s_waitcnt lgkmcnt(0)
	v_add_f32_e32 v236, v236, v233
	v_xor_b32_e32 v233, 64, v228
	ds_bpermute_b32 v233, v233, v236
	s_waitcnt lgkmcnt(0)
	v_add_f32_e32 v236, v236, v233
	v_xor_b32_e32 v233, 0x80, v228
	ds_bpermute_b32 v233, v233, v236
	s_waitcnt lgkmcnt(0)
	v_add_f32_e32 v236, v236, v233
	v_mul_f32_e32 v236, 0x3fb8aa3b, v236
	v_exp_f32_e32 v236, v236
	s_nop 0
	v_sub_f32_e32 v236, v235, v236
	v_add_f32_e32 v251, v189, v236
	s_mov_b64 s[76:77], exec
	v_readlane_b32 s78, v253, 4
	v_readlane_b32 s79, v253, 5
	s_and_b64 s[78:79], s[76:77], s[78:79]
	s_mov_b64 exec, s[78:79]
	s_cbranch_execz .Lpf_init
	global_atomic_add v249, v252, v219, s[20:21] offset:256 sc0
	s_waitcnt vmcnt(0)
.Lpf_init:
	s_mov_b64 exec, s[76:77]
	s_branch .LBB0_912
.Lpf_cont_stub:
	s_mov_b64 s[76:77], exec
	v_readlane_b32 s78, v253, 4
	v_readlane_b32 s79, v253, 5
	s_and_b64 s[78:79], s[76:77], s[78:79]
	s_mov_b64 exec, s[78:79]
	s_cbranch_execz .Lpf_cont
	global_atomic_add v249, v252, v219, s[20:21] offset:256 sc0
	s_waitcnt vmcnt(0)

; __global__ void __launch_bounds__(NTHR, 2) mega_fwd(KArgs a) {
;     ...
;             for (;;) {
;                 if (threadIdx.x == 0) MISC[16] = atomicAdd(qhead, 1u);
;                 __syncthreads();
;                 const int u = (int)MISC[16];
;                 __syncthreads();
.LBB0_912:
	s_mov_b64 s[0:1], exec
	v_readlane_b32 s4, v253, 4
	v_readlane_b32 s5, v253, 5
	s_and_b64 s[4:5], s[0:1], s[4:5]
	s_mov_b64 exec, s[4:5]
	s_cbranch_execz .LBB0_914
	v_readlane_b32 s4, v254, 10
	s_nop 1
	v_mov_b32_e32 v2, s4
	s_waitcnt vmcnt(8)
	ds_write_b32 v2, v249

; #define GAS __attribute__((address_space(1)))
; __device__ __forceinline__ float swapsum(float m) { auto rr = __builtin_amdgcn_permlane32_swap(__float_as_uint(m), __float_as_uint(m), false, false); return __uint_as_float(rr[0]) + __uint_as_float(rr[1]); }
; __device__ __forceinline__ unsigned cvtpk(float lo, float hi) { f32x2_t v = {lo, hi}; bf16x2_t b = __builtin_convertvector(v, bf16x2_t); return __builtin_bit_cast(unsigned, b); }
; template <int MODE> __device__ __forceinline__ void attn_unit4(LAS unsigned char* lds, const int uidx, const AttnArgs& A) {
;     ...
;     __builtin_amdgcn_s_setprio(0);
;     A2_PV(vs_prev, pk);
;     __syncthreads();
;     ...
;     float lt = swapsum(lsum);
;     if (MODE == 2) lt += __builtin_amdgcn_exp2f(A.sinks[2 * hx + st] * LOG2E - mref);
;     const float inv = 1.0f / lt;
; #pragma unroll
;     for (int d = 0; d < NDB; ++d)
; #pragma unroll
;         for (int r = 0; r < 16; ++r) o[d][r] *= inv;
;     ...
;     } else {
;         GAS bf16_t* op = (GAS bf16_t*)A.O + orow * DM + (MODE == 1 ? 768 : 512) + (2 * hx + st) * 64 + 4 * hi;
; #pragma unroll
;         for (int d = 0; d < NDB; ++d)
; #pragma unroll
;             for (int g4 = 0; g4 < 4; ++g4) {
;                 u32x2 w; w.x = cvtpk(o[d][4 * g4], o[d][4 * g4 + 1]); w.y = cvtpk(o[d][4 * g4 + 2], o[d][4 * g4 + 3]);
;                 *(GAS u32x2*)(op + d * 32 + 8 * g4) = w;
;             }
;     }
;     __syncthreads();
.LBB0_953:
	s_mov_b64 s[76:77], exec
	v_readlane_b32 s78, v253, 4
	v_readlane_b32 s79, v253, 5
	s_and_b64 s[78:79], s[76:77], s[78:79]
	s_mov_b64 exec, s[78:79]
	s_cbranch_execz .Lpf_m2
	global_atomic_add v249, v252, v219, s[20:21] offset:256 sc0
.Lpf_m2:
	s_mov_b64 exec, s[76:77]
	v_mov_b32_e32 v131, v1
	s_setprio 0
	s_mul_i32 s5, s26, 0x5000
	s_add_i32 s5, s5, 0
	v_add_u32_e32 v0, s5, v141
	ds_read_b64_tr_b16 v[34:35], v0 offset:51200
	ds_read_b64_tr_b16 v[36:37], v0 offset:53760
	v_add_u32_e32 v38, 0xc800, v0
	s_ashr_i32 s5, s4, 31
	s_lshl_b64 s[4:5], s[4:5], 2
	s_add_u32 s4, s68, s4
	s_waitcnt lgkmcnt(0)
	v_mfma_f32_32x32x16_bf16 v[2:17], v[34:37], v[102:105], v[2:17]
	ds_read_b64_tr_b16 v[34:35], v0 offset:56320
	ds_read_b64_tr_b16 v[36:37], v0 offset:58880
	s_addc_u32 s5, s89, s5
	s_waitcnt lgkmcnt(0)
	v_mfma_f32_32x32x16_bf16 v[2:17], v[34:37], v[98:101], v[2:17]
	ds_read_b64_tr_b16 v[34:35], v0 offset:61440
	ds_read_b64_tr_b16 v[36:37], v0 offset:64000
	s_waitcnt lgkmcnt(0)
	v_mfma_f32_32x32x16_bf16 v[2:17], v[34:37], v[110:113], v[2:17]
	ds_read_b64_tr_b16 v[34:35], v38 offset:15360
	ds_read_b64_tr_b16 v[36:37], v38 offset:17920
	s_waitcnt lgkmcnt(0)
	v_mfma_f32_32x32x16_bf16 v[2:17], v[34:37], v[106:109], v[2:17]
	ds_read_b64_tr_b16 v[34:35], v0 offset:51264
	ds_read_b64_tr_b16 v[36:37], v0 offset:53824
	s_waitcnt lgkmcnt(0)
	v_mfma_f32_32x32x16_bf16 v[18:33], v[34:37], v[102:105], v[18:33]
	ds_read_b64_tr_b16 v[34:35], v0 offset:56384
	ds_read_b64_tr_b16 v[36:37], v0 offset:58944
	s_waitcnt lgkmcnt(0)
	v_mfma_f32_32x32x16_bf16 v[18:33], v[34:37], v[98:101], v[18:33]
	ds_read_b64_tr_b16 v[34:35], v0 offset:61504
	ds_read_b64_tr_b16 v[36:37], v0 offset:64064
	v_mov_b32_e32 v0, v160
	s_nop 1
	v_permlane32_swap_b32_e32 v160, v0
	v_add_f32_e32 v0, v160, v0
	s_waitcnt lgkmcnt(0)
	v_mfma_f32_32x32x16_bf16 v[18:33], v[34:37], v[110:113], v[18:33]
	ds_read_b64_tr_b16 v[34:35], v38 offset:15424
	ds_read_b64_tr_b16 v[36:37], v38 offset:17984
	s_waitcnt lgkmcnt(0)
	s_barrier
	v_mfma_f32_32x32x16_bf16 v[18:33], v[34:37], v[106:109], v[18:33]
	global_load_dword v34, v1, s[4:5]
	s_mov_b32 s4, 0x3fb8aa3b
	s_waitcnt vmcnt(0)
	v_fma_f32 v34, v34, s4, -v143
	v_exp_f32_e32 v34, v34
	s_nop 0
	v_add_f32_e32 v0, v0, v34
	v_div_scale_f32 v34, s[4:5], v0, v0, 1.0
	v_rcp_f32_e32 v35, v34
	s_nop 0
	v_fma_f32 v36, -v34, v35, 1.0
	v_fmac_f32_e32 v35, v36, v35
	v_div_scale_f32 v36, vcc, 1.0, v0, 1.0
	v_mul_f32_e32 v37, v36, v35
	v_fma_f32 v38, -v34, v37, v36
	v_fmac_f32_e32 v37, v38, v35
	v_fma_f32 v34, -v34, v37, v36
	v_div_fmas_f32 v34, v34, v35, v37
	v_div_fixup_f32 v0, v34, v0, 1.0
	v_pk_mul_f32 v[34:35], v[14:15], v[0:1] op_sel_hi:[1,0]
	v_pk_mul_f32 v[14:15], v[18:19], v[0:1] op_sel_hi:[1,0]
	v_lshlrev_b64 v[18:19], 11, v[130:131]
	v_lshl_add_u64 v[18:19], s[10:11], 0, v[18:19]
	v_pk_mul_f32 v[46:47], v[2:3], v[0:1] op_sel_hi:[1,0]
	v_pk_mul_f32 v[48:49], v[4:5], v[0:1] op_sel_hi:[1,0]
	v_pk_mul_f32 v[42:43], v[6:7], v[0:1] op_sel_hi:[1,0]
	v_pk_mul_f32 v[44:45], v[8:9], v[0:1] op_sel_hi:[1,0]
	v_pk_mul_f32 v[38:39], v[10:11], v[0:1] op_sel_hi:[1,0]
	v_pk_mul_f32 v[40:41], v[12:13], v[0:1] op_sel_hi:[1,0]
	v_pk_mul_f32 v[36:37], v[16:17], v[0:1] op_sel_hi:[1,0]
	v_pk_mul_f32 v[16:17], v[20:21], v[0:1] op_sel_hi:[1,0]
	v_pk_mul_f32 v[10:11], v[22:23], v[0:1] op_sel_hi:[1,0]
	v_pk_mul_f32 v[12:13], v[24:25], v[0:1] op_sel_hi:[1,0]
	v_pk_mul_f32 v[6:7], v[26:27], v[0:1] op_sel_hi:[1,0]
	v_pk_mul_f32 v[8:9], v[28:29], v[0:1] op_sel_hi:[1,0]
	v_pk_mul_f32 v[2:3], v[30:31], v[0:1] op_sel_hi:[1,0]
	v_pk_mul_f32 v[4:5], v[32:33], v[0:1] op_sel_hi:[1,0]
	v_lshl_add_u64 v[18:19], s[0:1], 1, v[18:19]
	v_lshlrev_b32_e32 v0, 1, v133
	v_lshl_add_u64 v[18:19], v[18:19], 0, v[0:1]
	v_cvt_pk_bf16_f32 v20, v46, v47
	v_cvt_pk_bf16_f32 v21, v48, v49
	global_store_dwordx2 v[18:19], v[20:21], off offset:1024
	v_cvt_pk_bf16_f32 v20, v42, v43
	v_cvt_pk_bf16_f32 v21, v44, v45
	global_store_dwordx2 v[18:19], v[20:21], off offset:1040
	v_cvt_pk_bf16_f32 v20, v38, v39
	v_cvt_pk_bf16_f32 v21, v40, v41
	global_store_dwordx2 v[18:19], v[20:21], off offset:1056
	v_cvt_pk_bf16_f32 v20, v34, v35
	v_cvt_pk_bf16_f32 v21, v36, v37
	v_cvt_pk_bf16_f32 v14, v14, v15
	v_cvt_pk_bf16_f32 v15, v16, v17
	v_cvt_pk_bf16_f32 v10, v10, v11
	v_cvt_pk_bf16_f32 v11, v12, v13
	v_cvt_pk_bf16_f32 v6, v6, v7
	v_cvt_pk_bf16_f32 v7, v8, v9
	v_cvt_pk_bf16_f32 v2, v2, v3
	v_cvt_pk_bf16_f32 v3, v4, v5
	global_store_dwordx2 v[18:19], v[20:21], off offset:1072
	global_store_dwordx2 v[18:19], v[14:15], off offset:1088
	global_store_dwordx2 v[18:19], v[10:11], off offset:1104
	global_store_dwordx2 v[18:19], v[6:7], off offset:1120
	global_store_dwordx2 v[18:19], v[2:3], off offset:1136
	s_barrier
	s_mov_b64 s[0:1], 0

; template <int MODE> __device__ __forceinline__ void attn_unit4(LAS unsigned char* lds, const int uidx, const AttnArgs& A) {
;     ...
;     if (__any(fprev != 1.0f)) {
; #pragma unroll
;         for (int d = 0; d < NDB; ++d)
; #pragma unroll
;             for (int r = 0; r < 16; ++r) o[d][r] *= fprev;
;     }
;     __builtin_amdgcn_s_setprio(0);
;     A2_PV(vs_prev, pk);
.Lpf_m0:
	s_mov_b64 exec, s[76:77]
	v_fmac_f32_e32 v0, v163, v162
	s_setprio 0
	v_add_u32_e32 v78, 0x16800, v192
	ds_read_b64_tr_b16 v[74:75], v78
	ds_read_b64_tr_b16 v[76:77], v78 offset:2560
	s_cmp_lg_u32 s69, 1
	s_waitcnt lgkmcnt(0)
	v_mfma_f32_32x32x16_bf16 v[50:65], v[74:77], v[82:85], v[50:65]
	ds_read_b64_tr_b16 v[74:75], v78 offset:5120
	ds_read_b64_tr_b16 v[76:77], v78 offset:7680
	s_waitcnt lgkmcnt(0)
	v_mfma_f32_32x32x16_bf16 v[50:65], v[74:77], v[86:89], v[50:65]
	ds_read_b64_tr_b16 v[74:75], v78 offset:10240
	ds_read_b64_tr_b16 v[76:77], v78 offset:12800
	s_waitcnt lgkmcnt(0)
	v_mfma_f32_32x32x16_bf16 v[50:65], v[74:77], v[66:69], v[50:65]
	ds_read_b64_tr_b16 v[74:75], v78 offset:15360
	ds_read_b64_tr_b16 v[76:77], v78 offset:17920
	s_waitcnt lgkmcnt(0)
	v_mfma_f32_32x32x16_bf16 v[50:65], v[74:77], v[70:73], v[50:65]
	ds_read_b64_tr_b16 v[74:75], v78 offset:64
	ds_read_b64_tr_b16 v[76:77], v78 offset:2624
	s_waitcnt lgkmcnt(0)
	v_mfma_f32_32x32x16_bf16 v[34:49], v[74:77], v[82:85], v[34:49]
	ds_read_b64_tr_b16 v[74:75], v78 offset:5184
	ds_read_b64_tr_b16 v[76:77], v78 offset:7744
	s_waitcnt lgkmcnt(0)
	v_mfma_f32_32x32x16_bf16 v[34:49], v[74:77], v[86:89], v[34:49]
	ds_read_b64_tr_b16 v[74:75], v78 offset:10304
	ds_read_b64_tr_b16 v[76:77], v78 offset:12864
	s_waitcnt lgkmcnt(0)
	v_mfma_f32_32x32x16_bf16 v[34:49], v[74:77], v[66:69], v[34:49]
	ds_read_b64_tr_b16 v[74:75], v78 offset:15424
	ds_read_b64_tr_b16 v[76:77], v78 offset:17984
	s_waitcnt lgkmcnt(0)
	v_mfma_f32_32x32x16_bf16 v[34:49], v[74:77], v[70:73], v[34:49]
	ds_read_b64_tr_b16 v[74:75], v78 offset:128
	ds_read_b64_tr_b16 v[76:77], v78 offset:2688
	s_waitcnt lgkmcnt(0)
	v_mfma_f32_32x32x16_bf16 v[18:33], v[74:77], v[82:85], v[18:33]
	ds_read_b64_tr_b16 v[74:75], v78 offset:5248
	ds_read_b64_tr_b16 v[76:77], v78 offset:7808
	s_waitcnt lgkmcnt(0)
	v_mfma_f32_32x32x16_bf16 v[18:33], v[74:77], v[86:89], v[18:33]
	ds_read_b64_tr_b16 v[74:75], v78 offset:10368
	ds_read_b64_tr_b16 v[76:77], v78 offset:12928
	s_waitcnt lgkmcnt(0)
	v_mfma_f32_32x32x16_bf16 v[18:33], v[74:77], v[66:69], v[18:33]
	ds_read_b64_tr_b16 v[74:75], v78 offset:15488
	ds_read_b64_tr_b16 v[76:77], v78 offset:18048
	s_waitcnt lgkmcnt(0)
	v_mfma_f32_32x32x16_bf16 v[18:33], v[74:77], v[70:73], v[18:33]
	ds_read_b64_tr_b16 v[74:75], v78 offset:192
	ds_read_b64_tr_b16 v[76:77], v78 offset:2752
	s_waitcnt lgkmcnt(0)
	v_mfma_f32_32x32x16_bf16 v[2:17], v[74:77], v[82:85], v[2:17]
	ds_read_b64_tr_b16 v[74:75], v78 offset:5312
	ds_read_b64_tr_b16 v[76:77], v78 offset:7872
	s_waitcnt lgkmcnt(0)
	v_mfma_f32_32x32x16_bf16 v[2:17], v[74:77], v[86:89], v[2:17]
	ds_read_b64_tr_b16 v[74:75], v78 offset:10432
	ds_read_b64_tr_b16 v[76:77], v78 offset:12992
	s_waitcnt lgkmcnt(0)
	v_mfma_f32_32x32x16_bf16 v[2:17], v[74:77], v[66:69], v[2:17]
	ds_read_b64_tr_b16 v[66:67], v78 offset:15552
	ds_read_b64_tr_b16 v[68:69], v78 offset:18112
	s_waitcnt lgkmcnt(0)
	s_barrier
; #define LAS __attribute__((address_space(3)))
; __device__ __forceinline__ float swapsum(float m) { auto rr = __builtin_amdgcn_permlane32_swap(__float_as_uint(m), __float_as_uint(m), false, false); return __uint_as_float(rr[0]) + __uint_as_float(rr[1]); }
; template <int MODE> __device__ __forceinline__ void attn_unit4(LAS unsigned char* lds, const int uidx, const AttnArgs& A) {
;     ...
;     float lt = swapsum(lsum);
;     if (MODE == 2) lt += __builtin_amdgcn_exp2f(A.sinks[2 * hx + st] * LOG2E - mref);
;     const float inv = 1.0f / lt;
; #pragma unroll
;     for (int d = 0; d < NDB; ++d)
; #pragma unroll
;         for (int r = 0; r < 16; ++r) o[d][r] *= inv;
;     const size_t orow = row0 + qslot0 + r32;
;     if (MODE == 0) {
;         LAS float* X = (LAS float*)lds;
;         if (st == 1) {
; #pragma unroll
;             for (int d = 0; d < NDB; ++d)
; #pragma unroll
;                 for (int r = 0; r < 16; ++r) X[(qg * 64 + d * 16 + r) * 64 + lane] = o[d][r];
;         }
;         __syncthreads();
	v_mfma_f32_32x32x16_bf16 v[2:17], v[66:69], v[70:73], v[2:17]
	v_mov_b32_e32 v66, v0
	s_nop 1
	v_permlane32_swap_b32_e32 v0, v66
	v_add_f32_e32 v0, v0, v66
	v_div_scale_f32 v66, s[0:1], v0, v0, 1.0
	v_rcp_f32_e32 v67, v66
	s_nop 0
	v_fma_f32 v68, -v66, v67, 1.0
	v_fmac_f32_e32 v67, v68, v67
	v_div_scale_f32 v68, vcc, 1.0, v0, 1.0
	v_mul_f32_e32 v69, v68, v67
	v_fma_f32 v70, -v66, v69, v68
	v_fmac_f32_e32 v69, v70, v67
	v_fma_f32 v66, -v66, v69, v68
	v_div_fmas_f32 v66, v66, v67, v69
	v_div_fixup_f32 v0, v66, v0, 1.0
	v_pk_mul_f32 v[88:89], v[50:51], v[0:1] op_sel_hi:[1,0]
	v_pk_mul_f32 v[90:91], v[52:53], v[0:1] op_sel_hi:[1,0]
	v_pk_mul_f32 v[84:85], v[54:55], v[0:1] op_sel_hi:[1,0]
	v_pk_mul_f32 v[86:87], v[56:57], v[0:1] op_sel_hi:[1,0]
	v_pk_mul_f32 v[80:81], v[58:59], v[0:1] op_sel_hi:[1,0]
	v_pk_mul_f32 v[82:83], v[60:61], v[0:1] op_sel_hi:[1,0]
	v_pk_mul_f32 v[76:77], v[62:63], v[0:1] op_sel_hi:[1,0]
	v_pk_mul_f32 v[78:79], v[64:65], v[0:1] op_sel_hi:[1,0]
	v_pk_mul_f32 v[72:73], v[34:35], v[0:1] op_sel_hi:[1,0]
	v_pk_mul_f32 v[74:75], v[36:37], v[0:1] op_sel_hi:[1,0]
	v_pk_mul_f32 v[68:69], v[38:39], v[0:1] op_sel_hi:[1,0]
	v_pk_mul_f32 v[70:71], v[40:41], v[0:1] op_sel_hi:[1,0]
	v_pk_mul_f32 v[64:65], v[42:43], v[0:1] op_sel_hi:[1,0]
	v_pk_mul_f32 v[66:67], v[44:45], v[0:1] op_sel_hi:[1,0]
	v_pk_mul_f32 v[60:61], v[46:47], v[0:1] op_sel_hi:[1,0]
	v_pk_mul_f32 v[62:63], v[48:49], v[0:1] op_sel_hi:[1,0]
	v_pk_mul_f32 v[48:49], v[18:19], v[0:1] op_sel_hi:[1,0]
	v_pk_mul_f32 v[54:55], v[20:21], v[0:1] op_sel_hi:[1,0]
	v_pk_mul_f32 v[38:39], v[22:23], v[0:1] op_sel_hi:[1,0]
	v_pk_mul_f32 v[40:41], v[24:25], v[0:1] op_sel_hi:[1,0]
	v_pk_mul_f32 v[34:35], v[26:27], v[0:1] op_sel_hi:[1,0]
	v_pk_mul_f32 v[36:37], v[28:29], v[0:1] op_sel_hi:[1,0]
	v_pk_mul_f32 v[26:27], v[30:31], v[0:1] op_sel_hi:[1,0]
	v_pk_mul_f32 v[30:31], v[32:33], v[0:1] op_sel_hi:[1,0]
	v_pk_mul_f32 v[24:25], v[2:3], v[0:1] op_sel_hi:[1,0]
	v_pk_mul_f32 v[28:29], v[4:5], v[0:1] op_sel_hi:[1,0]
	v_pk_mul_f32 v[20:21], v[6:7], v[0:1] op_sel_hi:[1,0]
	v_pk_mul_f32 v[22:23], v[8:9], v[0:1] op_sel_hi:[1,0]
	v_pk_mul_f32 v[18:19], v[10:11], v[0:1] op_sel_hi:[1,0]
	v_pk_mul_f32 v[12:13], v[12:13], v[0:1] op_sel_hi:[1,0]
	v_pk_mul_f32 v[10:11], v[14:15], v[0:1] op_sel_hi:[1,0]
	v_pk_mul_f32 v[2:3], v[16:17], v[0:1] op_sel_hi:[1,0]
	s_cbranch_scc1 .Lgs_pre
	s_lshl_b32 s0, s65, 14
	s_add_i32 s0, s0, 0
	v_lshl_add_u32 v0, v177, 2, s0
	ds_write2st64_b32 v0, v88, v89 offset1:1
	ds_write2st64_b32 v0, v90, v91 offset0:2 offset1:3
	ds_write2st64_b32 v0, v84, v85 offset0:4 offset1:5
	ds_write2st64_b32 v0, v86, v87 offset0:6 offset1:7
	ds_write2st64_b32 v0, v80, v81 offset0:8 offset1:9
	ds_write2st64_b32 v0, v82, v83 offset0:10 offset1:11
	ds_write2st64_b32 v0, v76, v77 offset0:12 offset1:13
	ds_write2st64_b32 v0, v78, v79 offset0:14 offset1:15
	ds_write2st64_b32 v0, v72, v73 offset0:16 offset1:17
	ds_write2st64_b32 v0, v74, v75 offset0:18 offset1:19
	ds_write2st64_b32 v0, v68, v69 offset0:20 offset1:21
	ds_write2st64_b32 v0, v70, v71 offset0:22 offset1:23
	ds_write2st64_b32 v0, v64, v65 offset0:24 offset1:25
	ds_write2st64_b32 v0, v66, v67 offset0:26 offset1:27
	ds_write2st64_b32 v0, v60, v61 offset0:28 offset1:29
	ds_write2st64_b32 v0, v62, v63 offset0:30 offset1:31
	ds_write2st64_b32 v0, v48, v49 offset0:32 offset1:33
	ds_write2st64_b32 v0, v54, v55 offset0:34 offset1:35
	ds_write2st64_b32 v0, v38, v39 offset0:36 offset1:37
	ds_write2st64_b32 v0, v40, v41 offset0:38 offset1:39
	ds_write2st64_b32 v0, v34, v35 offset0:40 offset1:41
	ds_write2st64_b32 v0, v36, v37 offset0:42 offset1:43
	ds_write2st64_b32 v0, v26, v27 offset0:44 offset1:45
	ds_write2st64_b32 v0, v30, v31 offset0:46 offset1:47
	ds_write2st64_b32 v0, v24, v25 offset0:48 offset1:49
	ds_write2st64_b32 v0, v28, v29 offset0:50 offset1:51
	ds_write2st64_b32 v0, v20, v21 offset0:52 offset1:53
	ds_write2st64_b32 v0, v22, v23 offset0:54 offset1:55
	ds_write2st64_b32 v0, v18, v19 offset0:56 offset1:57
	ds_write2st64_b32 v0, v12, v13 offset0:58 offset1:59
	ds_write2st64_b32 v0, v10, v11 offset0:60 offset1:61
	ds_write2st64_b32 v0, v2, v3 offset0:62 offset1:63

; #define GAS __attribute__((address_space(1)))
; __device__ __forceinline__ float swapsum(float m) { auto rr = __builtin_amdgcn_permlane32_swap(__float_as_uint(m), __float_as_uint(m), false, false); return __uint_as_float(rr[0]) + __uint_as_float(rr[1]); }
; __device__ __forceinline__ unsigned cvtpk(float lo, float hi) { f32x2_t v = {lo, hi}; bf16x2_t b = __builtin_convertvector(v, bf16x2_t); return __builtin_bit_cast(unsigned, b); }
; template <int MODE> __device__ __forceinline__ void attn_unit4(LAS unsigned char* lds, const int uidx, const AttnArgs& A) {
;     ...
;     __builtin_amdgcn_s_setprio(0);
;     A2_PV(vs_prev, pk);
;     __syncthreads();
;     ...
;     float lt = swapsum(lsum);
;     if (MODE == 2) lt += __builtin_amdgcn_exp2f(A.sinks[2 * hx + st] * LOG2E - mref);
;     const float inv = 1.0f / lt;
; #pragma unroll
;     for (int d = 0; d < NDB; ++d)
; #pragma unroll
;         for (int r = 0; r < 16; ++r) o[d][r] *= inv;
;     ...
;     } else {
;         GAS bf16_t* op = (GAS bf16_t*)A.O + orow * DM + (MODE == 1 ? 768 : 512) + (2 * hx + st) * 64 + 4 * hi;
; #pragma unroll
;         for (int d = 0; d < NDB; ++d)
; #pragma unroll
;             for (int g4 = 0; g4 < 4; ++g4) {
;                 u32x2 w; w.x = cvtpk(o[d][4 * g4], o[d][4 * g4 + 1]); w.y = cvtpk(o[d][4 * g4 + 2], o[d][4 * g4 + 3]);
;                 *(GAS u32x2*)(op + d * 32 + 8 * g4) = w;
;             }
;     }
;     __syncthreads();
.Lpf_m1:
	s_mov_b64 exec, s[76:77]
	v_fmac_f32_e32 v42, v143, v142
	s_setprio 0
	v_add_u32_e32 v43, 0x16800, v197
	ds_read_b64_tr_b16 v[44:45], v43
	ds_read_b64_tr_b16 v[46:47], v43 offset:2560
	s_waitcnt lgkmcnt(0)
	v_mfma_f32_32x32x16_bf16 v[18:33], v[44:47], v[50:53], v[18:33]
	ds_read_b64_tr_b16 v[44:45], v43 offset:5120
	ds_read_b64_tr_b16 v[46:47], v43 offset:7680
	s_waitcnt lgkmcnt(0)
	v_mfma_f32_32x32x16_bf16 v[18:33], v[44:47], v[54:57], v[18:33]
	ds_read_b64_tr_b16 v[44:45], v43 offset:10240
	ds_read_b64_tr_b16 v[46:47], v43 offset:12800
	s_waitcnt lgkmcnt(0)
	v_mfma_f32_32x32x16_bf16 v[18:33], v[44:47], v[34:37], v[18:33]
	ds_read_b64_tr_b16 v[44:45], v43 offset:15360
	ds_read_b64_tr_b16 v[46:47], v43 offset:17920
	s_waitcnt lgkmcnt(0)
	v_mfma_f32_32x32x16_bf16 v[18:33], v[44:47], v[38:41], v[18:33]
	ds_read_b64_tr_b16 v[44:45], v43 offset:64
	ds_read_b64_tr_b16 v[46:47], v43 offset:2624
	s_waitcnt lgkmcnt(0)
	v_mfma_f32_32x32x16_bf16 v[2:17], v[44:47], v[50:53], v[2:17]
	ds_read_b64_tr_b16 v[44:45], v43 offset:5184
	ds_read_b64_tr_b16 v[46:47], v43 offset:7744
	s_waitcnt lgkmcnt(0)
	v_mfma_f32_32x32x16_bf16 v[2:17], v[44:47], v[54:57], v[2:17]
	ds_read_b64_tr_b16 v[44:45], v43 offset:10304
	ds_read_b64_tr_b16 v[46:47], v43 offset:12864
	s_waitcnt lgkmcnt(0)
	v_mfma_f32_32x32x16_bf16 v[2:17], v[44:47], v[34:37], v[2:17]
	ds_read_b64_tr_b16 v[34:35], v43 offset:15424
	ds_read_b64_tr_b16 v[36:37], v43 offset:17984
	s_waitcnt lgkmcnt(0)
	s_barrier
	v_mfma_f32_32x32x16_bf16 v[2:17], v[34:37], v[38:41], v[2:17]
	v_mov_b32_e32 v34, v42
	s_nop 1
	v_permlane32_swap_b32_e32 v42, v34
	v_add_f32_e32 v34, v42, v34
	v_div_scale_f32 v35, s[0:1], v34, v34, 1.0
	v_rcp_f32_e32 v36, v35
	s_lshl_b32 s0, s6, 6
	s_ashr_i32 s1, s0, 31
	v_fma_f32 v37, -v35, v36, 1.0
	v_fmac_f32_e32 v36, v37, v36
	v_div_scale_f32 v37, vcc, 1.0, v34, 1.0
	v_mul_f32_e32 v38, v37, v36
	v_fma_f32 v39, -v35, v38, v37
	v_fmac_f32_e32 v38, v39, v36
	v_fma_f32 v35, -v35, v38, v37
	v_div_fmas_f32 v35, v35, v36, v38
	v_div_fixup_f32 v34, v35, v34, 1.0
	v_pk_mul_f32 v[18:19], v[18:19], v[34:35] op_sel_hi:[1,0]
	v_pk_mul_f32 v[20:21], v[20:21], v[34:35] op_sel_hi:[1,0]
	v_pk_mul_f32 v[22:23], v[22:23], v[34:35] op_sel_hi:[1,0]
	v_pk_mul_f32 v[24:25], v[24:25], v[34:35] op_sel_hi:[1,0]
	v_pk_mul_f32 v[26:27], v[26:27], v[34:35] op_sel_hi:[1,0]
	v_pk_mul_f32 v[28:29], v[28:29], v[34:35] op_sel_hi:[1,0]
	v_pk_mul_f32 v[30:31], v[30:31], v[34:35] op_sel_hi:[1,0]
	v_pk_mul_f32 v[32:33], v[32:33], v[34:35] op_sel_hi:[1,0]
	v_pk_mul_f32 v[2:3], v[2:3], v[34:35] op_sel_hi:[1,0]
	v_pk_mul_f32 v[4:5], v[4:5], v[34:35] op_sel_hi:[1,0]
	v_pk_mul_f32 v[6:7], v[6:7], v[34:35] op_sel_hi:[1,0]
	v_pk_mul_f32 v[8:9], v[8:9], v[34:35] op_sel_hi:[1,0]
	v_pk_mul_f32 v[10:11], v[10:11], v[34:35] op_sel_hi:[1,0]
	v_pk_mul_f32 v[12:13], v[12:13], v[34:35] op_sel_hi:[1,0]
	v_pk_mul_f32 v[14:15], v[14:15], v[34:35] op_sel_hi:[1,0]
	v_pk_mul_f32 v[16:17], v[16:17], v[34:35] op_sel_hi:[1,0]
	v_lshlrev_b64 v[34:35], 11, v[0:1]
	v_lshl_add_u64 v[34:35], s[10:11], 0, v[34:35]
	v_lshl_add_u64 v[34:35], s[0:1], 1, v[34:35]
	v_lshlrev_b32_e32 v0, 1, v196
	v_lshl_add_u64 v[34:35], v[34:35], 0, v[0:1]
	v_cvt_pk_bf16_f32 v18, v18, v19
	v_cvt_pk_bf16_f32 v19, v20, v21
	v_cvt_pk_bf16_f32 v2, v2, v3
	v_cvt_pk_bf16_f32 v3, v4, v5
	global_store_dwordx2 v[34:35], v[18:19], off offset:1536
	v_cvt_pk_bf16_f32 v18, v22, v23
	v_cvt_pk_bf16_f32 v19, v24, v25
	global_store_dwordx2 v[34:35], v[2:3], off offset:1600
	v_cvt_pk_bf16_f32 v2, v6, v7
	v_cvt_pk_bf16_f32 v3, v8, v9
	global_store_dwordx2 v[34:35], v[18:19], off offset:1552
	v_cvt_pk_bf16_f32 v18, v26, v27
	v_cvt_pk_bf16_f32 v19, v28, v29
	global_store_dwordx2 v[34:35], v[2:3], off offset:1616
	v_cvt_pk_bf16_f32 v2, v10, v11
	v_cvt_pk_bf16_f32 v3, v12, v13
	global_store_dwordx2 v[34:35], v[18:19], off offset:1568
	v_cvt_pk_bf16_f32 v18, v30, v31
	v_cvt_pk_bf16_f32 v19, v32, v33
	global_store_dwordx2 v[34:35], v[2:3], off offset:1632
	v_cvt_pk_bf16_f32 v2, v14, v15
	v_cvt_pk_bf16_f32 v3, v16, v17
	global_store_dwordx2 v[34:35], v[18:19], off offset:1584
	global_store_dwordx2 v[34:35], v[2:3], off offset:1648
	s_barrier
	s_cbranch_execnz .LBB0_909
	s_branch .LBB0_971
